# conv-module LayerNorm: wave sums via DPP row ops and permlane swaps instead of ds_bpermute butterflies
# speedup vs baseline: 1.0258x; 1.0023x over previous
; __device__ __forceinline__ void convpool_phase(const Params& p, int l, LAS float* hb) {
;     ...
;         for (int qg = 0; qg < 2; ++qg) { const int tb = half * 16 + qg * 8;
;             float win[38];
; #pragma unroll
;             for (int i = 0; i < 38; ++i) win[i] = hb[(tb + i) * 256 + c];
; #pragma unroll
;             for (int q = 0; q < 8; ++q) { float a = bias;
; #pragma unroll
;                 for (int k = 0; k < 31; ++k) a += w[k] * win[q + k];
;                 ob[(tb + q) * 256 + c] = a; } }
.LBB0_488:
	v_cndmask_b32_e64 v10, 0, 1, s[0:1]
	v_cmp_ne_u32_e32 vcc, 1, v10
	v_or_b32_e32 v10, s2, v99
	v_lshl_add_u32 v48, v10, 10, v100
	ds_read2st64_b32 v[14:15], v48 offset1:4
	ds_read2st64_b32 v[16:17], v48 offset0:8 offset1:12
	ds_read2st64_b32 v[18:19], v48 offset0:16 offset1:20
	ds_read2st64_b32 v[20:21], v48 offset0:24 offset1:28
	ds_read2st64_b32 v[22:23], v48 offset0:32 offset1:36
	ds_read2st64_b32 v[24:25], v48 offset0:40 offset1:44
	ds_read2st64_b32 v[26:27], v48 offset0:48 offset1:52
	ds_read2st64_b32 v[28:29], v48 offset0:56 offset1:60
	ds_read2st64_b32 v[30:31], v48 offset0:64 offset1:68
	ds_read2st64_b32 v[32:33], v48 offset0:72 offset1:76
	ds_read2st64_b32 v[34:35], v48 offset0:80 offset1:84
	ds_read2st64_b32 v[36:37], v48 offset0:88 offset1:92
	ds_read2st64_b32 v[38:39], v48 offset0:96 offset1:100
	ds_read2st64_b32 v[40:41], v48 offset0:104 offset1:108
	ds_read2st64_b32 v[42:43], v48 offset0:112 offset1:116
	ds_read2st64_b32 v[44:45], v48 offset0:120 offset1:124
	ds_read2st64_b32 v[46:47], v48 offset0:128 offset1:132
	ds_read2st64_b32 v[12:13], v48 offset0:136 offset1:140
	ds_read2st64_b32 v[10:11], v48 offset0:144 offset1:148
	s_waitcnt lgkmcnt(0)
	v_fma_f32 v14, v66, v14, v97
	v_fmac_f32_e32 v14, v67, v15
	v_fma_f32 v15, v66, v15, v97
	v_fmac_f32_e32 v15, v67, v16
	v_fmac_f32_e32 v14, v68, v16
	v_fmac_f32_e32 v15, v68, v17
	v_fmac_f32_e32 v14, v69, v17
	v_fmac_f32_e32 v15, v69, v18
	v_fmac_f32_e32 v14, v70, v18
	v_fmac_f32_e32 v15, v70, v19
	v_fmac_f32_e32 v14, v71, v19
	v_fmac_f32_e32 v15, v71, v20
	v_fmac_f32_e32 v14, v72, v20
	v_fmac_f32_e32 v15, v72, v21
	v_fmac_f32_e32 v14, v73, v21
	v_fmac_f32_e32 v15, v73, v22
	v_fmac_f32_e32 v14, v74, v22
	v_fmac_f32_e32 v15, v74, v23
	v_fmac_f32_e32 v14, v75, v23
	v_fmac_f32_e32 v15, v75, v24
	v_fmac_f32_e32 v14, v76, v24
	v_fmac_f32_e32 v15, v76, v25
	v_fmac_f32_e32 v14, v77, v25
	v_fmac_f32_e32 v15, v77, v26
	v_fmac_f32_e32 v14, v78, v26
	v_fmac_f32_e32 v15, v78, v27
	v_fmac_f32_e32 v14, v79, v27
	v_fmac_f32_e32 v15, v79, v28
	v_fmac_f32_e32 v14, v80, v28
	v_fmac_f32_e32 v15, v80, v29
	v_fmac_f32_e32 v14, v81, v29
	v_fmac_f32_e32 v15, v81, v30
	v_fmac_f32_e32 v14, v82, v30
	v_fmac_f32_e32 v15, v82, v31
	v_fmac_f32_e32 v14, v83, v31
	v_fmac_f32_e32 v15, v83, v32
	v_fmac_f32_e32 v14, v84, v32
	v_fmac_f32_e32 v15, v84, v33
	v_fmac_f32_e32 v14, v85, v33
	v_fmac_f32_e32 v15, v85, v34
	v_fmac_f32_e32 v14, v86, v34
	v_fmac_f32_e32 v15, v86, v35
	v_fmac_f32_e32 v14, v87, v35
	v_fmac_f32_e32 v15, v87, v36
	v_fmac_f32_e32 v14, v88, v36
	v_fmac_f32_e32 v15, v88, v37
	v_fmac_f32_e32 v14, v89, v37
	v_fmac_f32_e32 v15, v89, v38
	v_fmac_f32_e32 v14, v90, v38
	v_fmac_f32_e32 v15, v90, v39
	v_fmac_f32_e32 v14, v91, v39
	v_fmac_f32_e32 v15, v91, v40
	v_fmac_f32_e32 v14, v92, v40
	v_fmac_f32_e32 v15, v92, v41
	v_fmac_f32_e32 v14, v93, v41
	v_fmac_f32_e32 v15, v93, v42
	v_fmac_f32_e32 v14, v94, v42
	v_fmac_f32_e32 v15, v94, v43
	v_fmac_f32_e32 v14, v95, v43
	v_fmac_f32_e32 v15, v95, v44
	v_fmac_f32_e32 v14, v96, v44
	v_fmac_f32_e32 v15, v96, v45
	ds_write2st64_b32 v48, v14, v15 offset0:248 offset1:252
	v_fma_f32 v14, v66, v16, v97
	v_fmac_f32_e32 v14, v67, v17
	v_fmac_f32_e32 v14, v68, v18
	v_fmac_f32_e32 v14, v69, v19
	v_fmac_f32_e32 v14, v70, v20
	v_fmac_f32_e32 v14, v71, v21
	v_fmac_f32_e32 v14, v72, v22
	v_fmac_f32_e32 v14, v73, v23
	v_fmac_f32_e32 v14, v74, v24
	v_fmac_f32_e32 v14, v75, v25
	v_fmac_f32_e32 v14, v76, v26
	v_fmac_f32_e32 v14, v77, v27
	v_fmac_f32_e32 v14, v78, v28
	v_fmac_f32_e32 v14, v79, v29
	v_fmac_f32_e32 v14, v80, v30
	v_fmac_f32_e32 v14, v81, v31
	v_fmac_f32_e32 v14, v82, v32
	v_fmac_f32_e32 v14, v83, v33
	v_fmac_f32_e32 v14, v84, v34
	v_fmac_f32_e32 v14, v85, v35
	v_fmac_f32_e32 v14, v86, v36
	v_fmac_f32_e32 v14, v87, v37
	v_fmac_f32_e32 v14, v88, v38
	v_fmac_f32_e32 v14, v89, v39
	v_fmac_f32_e32 v14, v90, v40
	v_fmac_f32_e32 v14, v91, v41
	v_fmac_f32_e32 v14, v92, v42
	v_fmac_f32_e32 v14, v93, v43
	v_fmac_f32_e32 v14, v94, v44
	v_fmac_f32_e32 v14, v95, v45
	v_add_u32_e32 v49, 0x800, v48
	v_fmac_f32_e32 v14, v96, v46
	ds_write_b32 v49, v14 offset:63488
	v_fma_f32 v14, v66, v17, v97
	v_fmac_f32_e32 v14, v67, v18
	v_fmac_f32_e32 v14, v68, v19
	v_fmac_f32_e32 v14, v69, v20
	v_fmac_f32_e32 v14, v70, v21
	v_fmac_f32_e32 v14, v71, v22
	v_fmac_f32_e32 v14, v72, v23
	v_fmac_f32_e32 v14, v73, v24
	v_fmac_f32_e32 v14, v74, v25
	v_fmac_f32_e32 v14, v75, v26
	v_fmac_f32_e32 v14, v76, v27
	v_fmac_f32_e32 v14, v77, v28
	v_fmac_f32_e32 v14, v78, v29
	v_fmac_f32_e32 v14, v79, v30
	v_fmac_f32_e32 v14, v80, v31
	v_fmac_f32_e32 v14, v81, v32
	v_fmac_f32_e32 v14, v82, v33
	v_fmac_f32_e32 v14, v83, v34
	v_fmac_f32_e32 v14, v84, v35
	v_fmac_f32_e32 v14, v85, v36
	v_fmac_f32_e32 v14, v86, v37
	v_fmac_f32_e32 v14, v87, v38
	v_fmac_f32_e32 v14, v88, v39
	v_fmac_f32_e32 v14, v89, v40
	v_fmac_f32_e32 v14, v90, v41
	v_fmac_f32_e32 v14, v91, v42
	v_fmac_f32_e32 v14, v92, v43
	v_fmac_f32_e32 v14, v93, v44
	v_fmac_f32_e32 v14, v94, v45
	v_fmac_f32_e32 v14, v95, v46
	v_add_u32_e32 v50, 0xc00, v48
	v_fmac_f32_e32 v14, v96, v47
	ds_write_b32 v50, v14 offset:63488
	v_fma_f32 v14, v66, v18, v97
	v_fmac_f32_e32 v14, v67, v19
	v_fmac_f32_e32 v14, v68, v20
	v_fmac_f32_e32 v14, v69, v21
	v_fmac_f32_e32 v14, v70, v22
	v_fmac_f32_e32 v14, v71, v23
	v_fmac_f32_e32 v14, v72, v24
	v_fmac_f32_e32 v14, v73, v25
	v_fmac_f32_e32 v14, v74, v26
	v_fmac_f32_e32 v14, v75, v27
	v_fmac_f32_e32 v14, v76, v28
	v_fmac_f32_e32 v14, v77, v29
	v_fmac_f32_e32 v14, v78, v30
	v_fmac_f32_e32 v14, v79, v31
	v_fmac_f32_e32 v14, v80, v32
	v_fmac_f32_e32 v14, v81, v33
	v_fmac_f32_e32 v14, v82, v34
	v_fmac_f32_e32 v14, v83, v35
; #define LAS __attribute__((address_space(3)))
; __device__ __forceinline__ void convpool_phase(const Params& p, int l, LAS float* hb) {
;     ...
;             for (int q = 0; q < 8; ++q) { float a = bias;
; #pragma unroll
;                 for (int k = 0; k < 31; ++k) a += w[k] * win[q + k];
;                 ob[(tb + q) * 256 + c] = a; } }
;         __syncthreads();
; #pragma unroll
;         for (int q = 0; q < 4; ++q) { const int tt = wid * 4 + q; f32x4 v = *(const LAS f32x4*)(ob + tt * 256 + lane * 4);
;             const float mean = wave_sum((v[0] + v[1]) + (v[2] + v[3])) * (1.0f / 256.0f);
;             v = v - mean;
;             const float var = wave_sum((v[0] * v[0] + v[1] * v[1]) + (v[2] * v[2] + v[3] * v[3])) * (1.0f / 256.0f);
;             const float rstd = 1.0f / sqrtf(var + LN_EPS);
	v_fmac_f32_e32 v14, v84, v36
	v_fmac_f32_e32 v14, v85, v37
	v_fmac_f32_e32 v14, v86, v38
	v_fmac_f32_e32 v14, v87, v39
	v_fmac_f32_e32 v14, v88, v40
	v_fmac_f32_e32 v14, v89, v41
	v_fmac_f32_e32 v14, v90, v42
	v_fmac_f32_e32 v14, v91, v43
	v_fmac_f32_e32 v14, v92, v44
	v_fmac_f32_e32 v14, v93, v45
	v_fmac_f32_e32 v14, v94, v46
	v_fmac_f32_e32 v14, v95, v47
	v_add_u32_e32 v51, 0x1000, v48
	v_fmac_f32_e32 v14, v96, v12
	ds_write_b32 v51, v14 offset:63488
	v_fma_f32 v14, v66, v19, v97
	v_fmac_f32_e32 v14, v67, v20
	v_fmac_f32_e32 v14, v68, v21
	v_fmac_f32_e32 v14, v69, v22
	v_fmac_f32_e32 v14, v70, v23
	v_fmac_f32_e32 v14, v71, v24
	v_fmac_f32_e32 v14, v72, v25
	v_fmac_f32_e32 v14, v73, v26
	v_fmac_f32_e32 v14, v74, v27
	v_fmac_f32_e32 v14, v75, v28
	v_fmac_f32_e32 v14, v76, v29
	v_fmac_f32_e32 v14, v77, v30
	v_fmac_f32_e32 v14, v78, v31
	v_fmac_f32_e32 v14, v79, v32
	v_fmac_f32_e32 v14, v80, v33
	v_fmac_f32_e32 v14, v81, v34
	v_fmac_f32_e32 v14, v82, v35
	v_fmac_f32_e32 v14, v83, v36
	v_fmac_f32_e32 v14, v84, v37
	v_fmac_f32_e32 v14, v85, v38
	v_fmac_f32_e32 v14, v86, v39
	v_fmac_f32_e32 v14, v87, v40
	v_fmac_f32_e32 v14, v88, v41
	v_fmac_f32_e32 v14, v89, v42
	v_fmac_f32_e32 v14, v90, v43
	v_fmac_f32_e32 v14, v91, v44
	v_fmac_f32_e32 v14, v92, v45
	v_fmac_f32_e32 v14, v93, v46
	v_fmac_f32_e32 v14, v94, v47
	v_fmac_f32_e32 v14, v95, v12
	v_add_u32_e32 v52, 0x1400, v48
	v_fmac_f32_e32 v14, v96, v13
	ds_write_b32 v52, v14 offset:63488
	v_fma_f32 v14, v66, v20, v97
	v_fmac_f32_e32 v14, v67, v21
	v_fmac_f32_e32 v14, v68, v22
	v_fmac_f32_e32 v14, v69, v23
	v_fmac_f32_e32 v14, v70, v24
	v_fmac_f32_e32 v14, v71, v25
	v_fmac_f32_e32 v14, v72, v26
	v_fmac_f32_e32 v14, v73, v27
	v_fmac_f32_e32 v14, v74, v28
	v_fmac_f32_e32 v14, v75, v29
	v_fmac_f32_e32 v14, v76, v30
	v_fmac_f32_e32 v14, v77, v31
	v_fmac_f32_e32 v14, v78, v32
	v_fmac_f32_e32 v14, v79, v33
	v_fmac_f32_e32 v14, v80, v34
	v_fmac_f32_e32 v14, v81, v35
	v_fmac_f32_e32 v14, v82, v36
	v_fmac_f32_e32 v14, v83, v37
	v_fmac_f32_e32 v14, v84, v38
	v_fmac_f32_e32 v14, v85, v39
	v_fmac_f32_e32 v14, v86, v40
	v_fmac_f32_e32 v14, v87, v41
	v_fmac_f32_e32 v14, v88, v42
	v_fmac_f32_e32 v14, v89, v43
	v_fmac_f32_e32 v14, v90, v44
	v_fmac_f32_e32 v14, v91, v45
	v_fmac_f32_e32 v14, v92, v46
	v_fmac_f32_e32 v14, v93, v47
	v_fmac_f32_e32 v14, v94, v12
	v_fmac_f32_e32 v14, v95, v13
	v_add_u32_e32 v53, 0x1800, v48
	v_fmac_f32_e32 v14, v96, v10
	ds_write_b32 v53, v14 offset:63488
	v_fma_f32 v14, v66, v21, v97
	v_fmac_f32_e32 v14, v67, v22
	v_fmac_f32_e32 v14, v68, v23
	v_fmac_f32_e32 v14, v69, v24
	v_fmac_f32_e32 v14, v70, v25
	v_fmac_f32_e32 v14, v71, v26
	v_fmac_f32_e32 v14, v72, v27
	v_fmac_f32_e32 v14, v73, v28
	v_fmac_f32_e32 v14, v74, v29
	v_fmac_f32_e32 v14, v75, v30
	v_fmac_f32_e32 v14, v76, v31
	v_fmac_f32_e32 v14, v77, v32
	v_fmac_f32_e32 v14, v78, v33
	v_fmac_f32_e32 v14, v79, v34
	v_fmac_f32_e32 v14, v80, v35
	v_fmac_f32_e32 v14, v81, v36
	v_fmac_f32_e32 v14, v82, v37
	v_fmac_f32_e32 v14, v83, v38
	v_fmac_f32_e32 v14, v84, v39
	v_fmac_f32_e32 v14, v85, v40
	v_fmac_f32_e32 v14, v86, v41
	v_fmac_f32_e32 v14, v87, v42
	v_fmac_f32_e32 v14, v88, v43
	v_fmac_f32_e32 v14, v89, v44
	v_fmac_f32_e32 v14, v90, v45
	v_fmac_f32_e32 v14, v91, v46
	v_fmac_f32_e32 v14, v92, v47
	v_fmac_f32_e32 v14, v93, v12
	v_fmac_f32_e32 v14, v94, v13
	v_fmac_f32_e32 v14, v95, v10
	v_add_u32_e32 v133, 0x1c00, v48
	v_fmac_f32_e32 v14, v96, v11
	s_mov_b32 s2, 8
	s_mov_b64 s[0:1], 0
	ds_write_b32 v133, v14 offset:63488
	s_cbranch_vccz .LBB0_488
	s_waitcnt lgkmcnt(0)
	s_barrier
	ds_read_b128 v[10:13], v128 offset:63488
	s_mov_b32 s2, 0xf800000
	s_add_i32 s24, s24, s23
	v_add_u32_e32 v122, s25, v122
	v_add_u32_e32 v123, s25, v123
	s_waitcnt lgkmcnt(0)
	v_mov_b32_e32 v14, v11
	v_mov_b32_e32 v15, v12
	v_mov_b32_e32 v16, v10
	v_mov_b32_e32 v17, v13
	v_pk_add_f32 v[14:15], v[14:15], v[16:17]
	v_add_u32_e32 v124, s25, v124
	v_add_f32_e32 v14, v14, v15
	s_cmpk_gt_i32 s24, 0x3ff
	s_nop 1
	v_add_f32_dpp v14, v14, v14 quad_perm:[1,0,3,2] row_mask:0xf bank_mask:0xf
	s_nop 1
	v_add_f32_dpp v14, v14, v14 quad_perm:[2,3,0,1] row_mask:0xf bank_mask:0xf
	s_nop 1
	v_add_f32_dpp v14, v14, v14 row_half_mirror row_mask:0xf bank_mask:0xf
	s_nop 1
	v_add_f32_dpp v14, v14, v14 row_mirror row_mask:0xf bank_mask:0xf
	v_mov_b32_e32 v15, v14
	s_nop 1
	v_permlane16_swap_b32_e32 v14, v15
	v_add_f32_e32 v14, v14, v15
	v_mov_b32_e32 v15, v14
	s_nop 1
	v_permlane32_swap_b32_e32 v14, v15
	v_add_f32_e32 v14, v14, v15
	s_waitcnt lgkmcnt(0)
	v_fmamk_f32 v11, v14, 0xbb800000, v11
	v_fmamk_f32 v10, v14, 0xbb800000, v10
	v_fmamk_f32 v13, v14, 0xbb800000, v13
	v_fmac_f32_e32 v12, 0xbb800000, v14
	v_pk_mul_f32 v[14:15], v[12:13], v[12:13]
	v_pk_mul_f32 v[16:17], v[10:11], v[10:11]
	s_nop 0
	v_pk_mov_b32 v[18:19], v[16:17], v[14:15] op_sel:[1,0]
	v_mov_b32_e32 v17, v15
	v_pk_add_f32 v[14:15], v[18:19], v[16:17]
	s_nop 0
	v_add_f32_e32 v14, v14, v15
	s_nop 1
	v_add_f32_dpp v14, v14, v14 quad_perm:[1,0,3,2] row_mask:0xf bank_mask:0xf
	s_nop 1
	v_add_f32_dpp v14, v14, v14 quad_perm:[2,3,0,1] row_mask:0xf bank_mask:0xf
	s_nop 1
	v_add_f32_dpp v14, v14, v14 row_half_mirror row_mask:0xf bank_mask:0xf
	s_nop 1
	v_add_f32_dpp v14, v14, v14 row_mirror row_mask:0xf bank_mask:0xf
	v_mov_b32_e32 v15, v14
	s_nop 1
	v_permlane16_swap_b32_e32 v14, v15
	v_add_f32_e32 v14, v14, v15
	v_mov_b32_e32 v15, v14
	s_nop 1
	v_permlane32_swap_b32_e32 v14, v15
	v_add_f32_e32 v14, v14, v15
	s_waitcnt lgkmcnt(0)
; #define LAS __attribute__((address_space(3)))
; __device__ __forceinline__ unsigned cvtpk(float lo, float hi) { f32x2 v = {lo, hi}; half2v h = __builtin_convertvector(v, half2v); return __builtin_bit_cast(unsigned, h); }
; __device__ __forceinline__ float sigmoidf_(float x) { return __builtin_amdgcn_rcpf(1.0f + __expf(-x)); }
; __device__ __forceinline__ void convpool_phase(const Params& p, int l, LAS float* hb) {
;     ...
;         for (int q = 0; q < 4; ++q) { const int tt = wid * 4 + q; f32x4 v = *(const LAS f32x4*)(ob + tt * 256 + lane * 4);
;             const float mean = wave_sum((v[0] + v[1]) + (v[2] + v[3])) * (1.0f / 256.0f);
;             v = v - mean;
;             const float var = wave_sum((v[0] * v[0] + v[1] * v[1]) + (v[2] * v[2] + v[3] * v[3])) * (1.0f / 256.0f);
;             const float rstd = 1.0f / sqrtf(var + LN_EPS);
;             f32x4 y = v * rstd * gcn + bcn;
; #pragma unroll
;             for (int e = 0; e < 4; ++e) y[e] = y[e] * sigmoidf_(y[e]);
;             u32x2 o2; o2.x = cvtpk(y[0], y[1]); o2.y = cvtpk(y[2], y[3]);
;             *(u32x2*)(CAT + (size_t)(t0 + tt) * LDC + lane * 4) = o2; }
	v_fmamk_f32 v14, v14, 0x3b800000, v235
	v_cmp_gt_f32_e32 vcc, s2, v14
	v_mul_f32_e32 v15, 0x4f800000, v14
	s_nop 0
	v_cndmask_b32_e32 v14, v14, v15, vcc
	v_sqrt_f32_e32 v15, v14
	s_nop 0
	v_add_u32_e32 v16, -1, v15
	v_fma_f32 v17, -v16, v15, v14
	v_cmp_ge_f32_e64 s[0:1], 0, v17
	v_add_u32_e32 v17, 1, v15
	s_nop 0
	v_cndmask_b32_e64 v16, v15, v16, s[0:1]
	v_fma_f32 v15, -v17, v15, v14
	v_cmp_lt_f32_e64 s[0:1], 0, v15
	s_nop 1
	v_cndmask_b32_e64 v15, v16, v17, s[0:1]
	v_mul_f32_e32 v16, 0x37800000, v15
	v_cndmask_b32_e32 v15, v15, v16, vcc
	v_cmp_class_f32_e32 vcc, v14, v232
	s_nop 1
	v_cndmask_b32_e32 v14, v15, v14, vcc
	v_div_scale_f32 v15, s[0:1], v14, v14, 1.0
	v_rcp_f32_e32 v16, v15
	s_nop 0
	v_fma_f32 v17, -v15, v16, 1.0
	v_fmac_f32_e32 v16, v17, v16
	v_div_scale_f32 v17, vcc, 1.0, v14, 1.0
	v_mul_f32_e32 v18, v17, v16
	v_fma_f32 v19, -v15, v18, v17
	v_fmac_f32_e32 v18, v19, v16
	v_fma_f32 v15, -v15, v18, v17
	v_div_fmas_f32 v15, v15, v16, v18
	v_div_fixup_f32 v14, v15, v14, 1.0
	v_pk_mul_f32 v[10:11], v[10:11], v[14:15] op_sel_hi:[1,0]
	v_pk_mul_f32 v[12:13], v[12:13], v[14:15] op_sel_hi:[1,0]
	v_pk_fma_f32 v[10:11], v[2:3], v[10:11], v[6:7]
	v_pk_fma_f32 v[12:13], v[4:5], v[12:13], v[8:9]
	v_mul_f32_e32 v14, 0xbfb8aa3b, v10
	v_mul_f32_e32 v15, 0xbfb8aa3b, v11
	v_exp_f32_e32 v14, v14
	v_exp_f32_e32 v15, v15
	v_add_f32_e32 v14, 1.0, v14
	v_add_f32_e32 v15, 1.0, v15
	v_rcp_f32_e32 v14, v14
	v_rcp_f32_e32 v15, v15
	s_nop 0
	v_pk_mul_f32 v[10:11], v[10:11], v[14:15]
	v_mul_f32_e32 v14, 0xbfb8aa3b, v12
	v_mul_f32_e32 v15, 0xbfb8aa3b, v13
	v_exp_f32_e32 v14, v14
	v_exp_f32_e32 v15, v15
	v_cvt_pk_f16_f32 v10, v10, v11
	v_add_f32_e32 v14, 1.0, v14
	v_add_f32_e32 v15, 1.0, v15
	v_rcp_f32_e32 v14, v14
	v_rcp_f32_e32 v15, v15
	s_nop 0
	v_pk_mul_f32 v[12:13], v[12:13], v[14:15]
	s_nop 0
	v_cvt_pk_f16_f32 v11, v12, v13
	v_add_u32_e32 v12, s50, v101
	v_ashrrev_i32_e32 v13, 31, v12
	v_lshlrev_b64 v[12:13], 11, v[12:13]
	v_lshl_add_u64 v[12:13], v[60:61], 0, v[12:13]
	flat_store_dwordx2 v[12:13], v[10:11]
	ds_read_b128 v[10:13], v129 offset:63488
	s_waitcnt lgkmcnt(0)
	v_mov_b32_e32 v14, v11
	v_mov_b32_e32 v15, v12
	v_mov_b32_e32 v16, v10
	v_mov_b32_e32 v17, v13
	v_pk_add_f32 v[14:15], v[14:15], v[16:17]
	s_nop 0
	v_add_f32_e32 v14, v14, v15
	s_nop 1
	v_add_f32_dpp v14, v14, v14 quad_perm:[1,0,3,2] row_mask:0xf bank_mask:0xf
	s_nop 1
	v_add_f32_dpp v14, v14, v14 quad_perm:[2,3,0,1] row_mask:0xf bank_mask:0xf
	s_nop 1
	v_add_f32_dpp v14, v14, v14 row_half_mirror row_mask:0xf bank_mask:0xf
	s_nop 1
	v_add_f32_dpp v14, v14, v14 row_mirror row_mask:0xf bank_mask:0xf
	v_mov_b32_e32 v15, v14
	s_nop 1
	v_permlane16_swap_b32_e32 v14, v15
	v_add_f32_e32 v14, v14, v15
	v_mov_b32_e32 v15, v14
	s_nop 1
	v_permlane32_swap_b32_e32 v14, v15
	v_add_f32_e32 v14, v14, v15
	s_waitcnt lgkmcnt(0)
	v_fmamk_f32 v11, v14, 0xbb800000, v11
	v_fmamk_f32 v10, v14, 0xbb800000, v10
	v_fmamk_f32 v13, v14, 0xbb800000, v13
	v_fmac_f32_e32 v12, 0xbb800000, v14
	v_pk_mul_f32 v[14:15], v[12:13], v[12:13]
	v_pk_mul_f32 v[16:17], v[10:11], v[10:11]
	s_nop 0
	v_pk_mov_b32 v[18:19], v[16:17], v[14:15] op_sel:[1,0]
	v_mov_b32_e32 v17, v15
	v_pk_add_f32 v[14:15], v[18:19], v[16:17]
	s_nop 0
	v_add_f32_e32 v14, v14, v15
	s_nop 1
	v_add_f32_dpp v14, v14, v14 quad_perm:[1,0,3,2] row_mask:0xf bank_mask:0xf
	s_nop 1
	v_add_f32_dpp v14, v14, v14 quad_perm:[2,3,0,1] row_mask:0xf bank_mask:0xf
	s_nop 1
	v_add_f32_dpp v14, v14, v14 row_half_mirror row_mask:0xf bank_mask:0xf
	s_nop 1
	v_add_f32_dpp v14, v14, v14 row_mirror row_mask:0xf bank_mask:0xf
	v_mov_b32_e32 v15, v14
	s_nop 1
	v_permlane16_swap_b32_e32 v14, v15
	v_add_f32_e32 v14, v14, v15
	v_mov_b32_e32 v15, v14
	s_nop 1
	v_permlane32_swap_b32_e32 v14, v15
	v_add_f32_e32 v14, v14, v15
	s_waitcnt lgkmcnt(0)
	v_fmamk_f32 v14, v14, 0x3b800000, v235
	v_cmp_gt_f32_e32 vcc, s2, v14
	v_mul_f32_e32 v15, 0x4f800000, v14
	s_nop 0
	v_cndmask_b32_e32 v14, v14, v15, vcc
	v_sqrt_f32_e32 v15, v14
	s_nop 0
	v_add_u32_e32 v16, -1, v15
	v_fma_f32 v17, -v16, v15, v14
	v_cmp_ge_f32_e64 s[0:1], 0, v17
	v_add_u32_e32 v17, 1, v15
	s_nop 0
	v_cndmask_b32_e64 v16, v15, v16, s[0:1]
	v_fma_f32 v15, -v17, v15, v14
	v_cmp_lt_f32_e64 s[0:1], 0, v15
	s_nop 1
	v_cndmask_b32_e64 v15, v16, v17, s[0:1]
	v_mul_f32_e32 v16, 0x37800000, v15
	v_cndmask_b32_e32 v15, v15, v16, vcc
	v_cmp_class_f32_e32 vcc, v14, v232
	s_nop 1
	v_cndmask_b32_e32 v14, v15, v14, vcc
	v_div_scale_f32 v15, s[0:1], v14, v14, 1.0
	v_rcp_f32_e32 v16, v15
	s_nop 0
	v_fma_f32 v17, -v15, v16, 1.0
	v_fmac_f32_e32 v16, v17, v16
	v_div_scale_f32 v17, vcc, 1.0, v14, 1.0
	v_mul_f32_e32 v18, v17, v16
	v_fma_f32 v19, -v15, v18, v17
	v_fmac_f32_e32 v18, v19, v16
	v_fma_f32 v15, -v15, v18, v17
	v_div_fmas_f32 v15, v15, v16, v18
	v_div_fixup_f32 v14, v15, v14, 1.0
	v_pk_mul_f32 v[10:11], v[10:11], v[14:15] op_sel_hi:[1,0]
	v_pk_mul_f32 v[12:13], v[12:13], v[14:15] op_sel_hi:[1,0]
	v_pk_fma_f32 v[10:11], v[2:3], v[10:11], v[6:7]
	v_pk_fma_f32 v[12:13], v[4:5], v[12:13], v[8:9]
	v_mul_f32_e32 v14, 0xbfb8aa3b, v10
	v_mul_f32_e32 v15, 0xbfb8aa3b, v11
	v_exp_f32_e32 v14, v14
	v_exp_f32_e32 v15, v15
	v_add_f32_e32 v14, 1.0, v14
	v_add_f32_e32 v15, 1.0, v15
	v_rcp_f32_e32 v14, v14
	v_rcp_f32_e32 v15, v15
	s_nop 0
	v_pk_mul_f32 v[10:11], v[10:11], v[14:15]
	v_mul_f32_e32 v14, 0xbfb8aa3b, v12
	v_mul_f32_e32 v15, 0xbfb8aa3b, v13
	v_exp_f32_e32 v14, v14
	v_exp_f32_e32 v15, v15
	v_cvt_pk_f16_f32 v10, v10, v11
	v_add_f32_e32 v14, 1.0, v14
	v_add_f32_e32 v15, 1.0, v15
	v_rcp_f32_e32 v14, v14
	v_rcp_f32_e32 v15, v15
	s_nop 0
	v_pk_mul_f32 v[12:13], v[12:13], v[14:15]
	s_nop 0
	v_cvt_pk_f16_f32 v11, v12, v13
	v_add_u32_e32 v12, s50, v119
	v_ashrrev_i32_e32 v13, 31, v12
	v_lshlrev_b64 v[12:13], 11, v[12:13]
	v_lshl_add_u64 v[12:13], v[60:61], 0, v[12:13]
	flat_store_dwordx2 v[12:13], v[10:11]
	ds_read_b128 v[10:13], v130 offset:63488
	s_waitcnt lgkmcnt(0)
; #define LAS __attribute__((address_space(3)))
; __device__ __forceinline__ unsigned cvtpk(float lo, float hi) { f32x2 v = {lo, hi}; half2v h = __builtin_convertvector(v, half2v); return __builtin_bit_cast(unsigned, h); }
; __device__ __forceinline__ float sigmoidf_(float x) { return __builtin_amdgcn_rcpf(1.0f + __expf(-x)); }
; __device__ __forceinline__ void convpool_phase(const Params& p, int l, LAS float* hb) {
;     ...
;         for (int q = 0; q < 4; ++q) { const int tt = wid * 4 + q; f32x4 v = *(const LAS f32x4*)(ob + tt * 256 + lane * 4);
;             const float mean = wave_sum((v[0] + v[1]) + (v[2] + v[3])) * (1.0f / 256.0f);
;             v = v - mean;
;             const float var = wave_sum((v[0] * v[0] + v[1] * v[1]) + (v[2] * v[2] + v[3] * v[3])) * (1.0f / 256.0f);
;             const float rstd = 1.0f / sqrtf(var + LN_EPS);
;             f32x4 y = v * rstd * gcn + bcn;
; #pragma unroll
;             for (int e = 0; e < 4; ++e) y[e] = y[e] * sigmoidf_(y[e]);
;             u32x2 o2; o2.x = cvtpk(y[0], y[1]); o2.y = cvtpk(y[2], y[3]);
;             *(u32x2*)(CAT + (size_t)(t0 + tt) * LDC + lane * 4) = o2; }
	v_mov_b32_e32 v14, v11
	v_mov_b32_e32 v15, v12
	v_mov_b32_e32 v16, v10
	v_mov_b32_e32 v17, v13
	v_pk_add_f32 v[14:15], v[14:15], v[16:17]
	s_nop 0
	v_add_f32_e32 v14, v14, v15
	s_nop 1
	v_add_f32_dpp v14, v14, v14 quad_perm:[1,0,3,2] row_mask:0xf bank_mask:0xf
	s_nop 1
	v_add_f32_dpp v14, v14, v14 quad_perm:[2,3,0,1] row_mask:0xf bank_mask:0xf
	s_nop 1
	v_add_f32_dpp v14, v14, v14 row_half_mirror row_mask:0xf bank_mask:0xf
	s_nop 1
	v_add_f32_dpp v14, v14, v14 row_mirror row_mask:0xf bank_mask:0xf
	v_mov_b32_e32 v15, v14
	s_nop 1
	v_permlane16_swap_b32_e32 v14, v15
	v_add_f32_e32 v14, v14, v15
	v_mov_b32_e32 v15, v14
	s_nop 1
	v_permlane32_swap_b32_e32 v14, v15
	v_add_f32_e32 v14, v14, v15
	s_waitcnt lgkmcnt(0)
	v_fmamk_f32 v11, v14, 0xbb800000, v11
	v_fmamk_f32 v10, v14, 0xbb800000, v10
	v_fmamk_f32 v13, v14, 0xbb800000, v13
	v_fmac_f32_e32 v12, 0xbb800000, v14
	v_pk_mul_f32 v[14:15], v[12:13], v[12:13]
	v_pk_mul_f32 v[16:17], v[10:11], v[10:11]
	s_nop 0
	v_pk_mov_b32 v[18:19], v[16:17], v[14:15] op_sel:[1,0]
	v_mov_b32_e32 v17, v15
	v_pk_add_f32 v[14:15], v[18:19], v[16:17]
	s_nop 0
	v_add_f32_e32 v14, v14, v15
	s_nop 1
	v_add_f32_dpp v14, v14, v14 quad_perm:[1,0,3,2] row_mask:0xf bank_mask:0xf
	s_nop 1
	v_add_f32_dpp v14, v14, v14 quad_perm:[2,3,0,1] row_mask:0xf bank_mask:0xf
	s_nop 1
	v_add_f32_dpp v14, v14, v14 row_half_mirror row_mask:0xf bank_mask:0xf
	s_nop 1
	v_add_f32_dpp v14, v14, v14 row_mirror row_mask:0xf bank_mask:0xf
	v_mov_b32_e32 v15, v14
	s_nop 1
	v_permlane16_swap_b32_e32 v14, v15
	v_add_f32_e32 v14, v14, v15
	v_mov_b32_e32 v15, v14
	s_nop 1
	v_permlane32_swap_b32_e32 v14, v15
	v_add_f32_e32 v14, v14, v15
	s_waitcnt lgkmcnt(0)
	v_fmamk_f32 v14, v14, 0x3b800000, v235
	v_cmp_gt_f32_e32 vcc, s2, v14
	v_mul_f32_e32 v15, 0x4f800000, v14
	s_nop 0
	v_cndmask_b32_e32 v14, v14, v15, vcc
	v_sqrt_f32_e32 v15, v14
	s_nop 0
	v_add_u32_e32 v16, -1, v15
	v_fma_f32 v17, -v16, v15, v14
	v_cmp_ge_f32_e64 s[0:1], 0, v17
	v_add_u32_e32 v17, 1, v15
	s_nop 0
	v_cndmask_b32_e64 v16, v15, v16, s[0:1]
	v_fma_f32 v15, -v17, v15, v14
	v_cmp_lt_f32_e64 s[0:1], 0, v15
	s_nop 1
	v_cndmask_b32_e64 v15, v16, v17, s[0:1]
	v_mul_f32_e32 v16, 0x37800000, v15
	v_cndmask_b32_e32 v15, v15, v16, vcc
	v_cmp_class_f32_e32 vcc, v14, v232
	s_nop 1
	v_cndmask_b32_e32 v14, v15, v14, vcc
	v_div_scale_f32 v15, s[0:1], v14, v14, 1.0
	v_rcp_f32_e32 v16, v15
	s_nop 0
	v_fma_f32 v17, -v15, v16, 1.0
	v_fmac_f32_e32 v16, v17, v16
	v_div_scale_f32 v17, vcc, 1.0, v14, 1.0
	v_mul_f32_e32 v18, v17, v16
	v_fma_f32 v19, -v15, v18, v17
	v_fmac_f32_e32 v18, v19, v16
	v_fma_f32 v15, -v15, v18, v17
	v_div_fmas_f32 v15, v15, v16, v18
	v_div_fixup_f32 v14, v15, v14, 1.0
	v_pk_mul_f32 v[10:11], v[10:11], v[14:15] op_sel_hi:[1,0]
	v_pk_mul_f32 v[12:13], v[12:13], v[14:15] op_sel_hi:[1,0]
	v_pk_fma_f32 v[10:11], v[2:3], v[10:11], v[6:7]
	v_pk_fma_f32 v[12:13], v[4:5], v[12:13], v[8:9]
	v_mul_f32_e32 v14, 0xbfb8aa3b, v10
	v_mul_f32_e32 v15, 0xbfb8aa3b, v11
	v_exp_f32_e32 v14, v14
	v_exp_f32_e32 v15, v15
	v_add_f32_e32 v14, 1.0, v14
	v_add_f32_e32 v15, 1.0, v15
	v_rcp_f32_e32 v14, v14
	v_rcp_f32_e32 v15, v15
	s_nop 0
	v_pk_mul_f32 v[10:11], v[10:11], v[14:15]
	v_mul_f32_e32 v14, 0xbfb8aa3b, v12
	v_mul_f32_e32 v15, 0xbfb8aa3b, v13
	v_exp_f32_e32 v14, v14
	v_exp_f32_e32 v15, v15
	v_cvt_pk_f16_f32 v10, v10, v11
	v_add_f32_e32 v14, 1.0, v14
	v_add_f32_e32 v15, 1.0, v15
	v_rcp_f32_e32 v14, v14
	v_rcp_f32_e32 v15, v15
	s_nop 0
	v_pk_mul_f32 v[12:13], v[12:13], v[14:15]
	s_nop 0
	v_cvt_pk_f16_f32 v11, v12, v13
	v_add_u32_e32 v12, s50, v120
	v_ashrrev_i32_e32 v13, 31, v12
	v_lshlrev_b64 v[12:13], 11, v[12:13]
	v_lshl_add_u64 v[12:13], v[60:61], 0, v[12:13]
	flat_store_dwordx2 v[12:13], v[10:11]
	ds_read_b128 v[10:13], v131 offset:63488
	s_waitcnt lgkmcnt(0)
; #define LAS __attribute__((address_space(3)))
; __device__ __forceinline__ unsigned cvtpk(float lo, float hi) { f32x2 v = {lo, hi}; half2v h = __builtin_convertvector(v, half2v); return __builtin_bit_cast(unsigned, h); }
; __device__ __forceinline__ float sigmoidf_(float x) { return __builtin_amdgcn_rcpf(1.0f + __expf(-x)); }
; __device__ __forceinline__ void convpool_phase(const Params& p, int l, LAS float* hb) {
;     ...
;         for (int q = 0; q < 4; ++q) { const int tt = wid * 4 + q; f32x4 v = *(const LAS f32x4*)(ob + tt * 256 + lane * 4);
;             const float mean = wave_sum((v[0] + v[1]) + (v[2] + v[3])) * (1.0f / 256.0f);
;             v = v - mean;
;             const float var = wave_sum((v[0] * v[0] + v[1] * v[1]) + (v[2] * v[2] + v[3] * v[3])) * (1.0f / 256.0f);
;             const float rstd = 1.0f / sqrtf(var + LN_EPS);
;             f32x4 y = v * rstd * gcn + bcn;
; #pragma unroll
;             for (int e = 0; e < 4; ++e) y[e] = y[e] * sigmoidf_(y[e]);
;             u32x2 o2; o2.x = cvtpk(y[0], y[1]); o2.y = cvtpk(y[2], y[3]);
;             *(u32x2*)(CAT + (size_t)(t0 + tt) * LDC + lane * 4) = o2; }
;         __syncthreads();
	v_mov_b32_e32 v14, v11
	v_mov_b32_e32 v15, v12
	v_mov_b32_e32 v16, v10
	v_mov_b32_e32 v17, v13
	v_pk_add_f32 v[14:15], v[14:15], v[16:17]
	s_nop 0
	v_add_f32_e32 v14, v14, v15
	s_nop 1
	v_add_f32_dpp v14, v14, v14 quad_perm:[1,0,3,2] row_mask:0xf bank_mask:0xf
	s_nop 1
	v_add_f32_dpp v14, v14, v14 quad_perm:[2,3,0,1] row_mask:0xf bank_mask:0xf
	s_nop 1
	v_add_f32_dpp v14, v14, v14 row_half_mirror row_mask:0xf bank_mask:0xf
	s_nop 1
	v_add_f32_dpp v14, v14, v14 row_mirror row_mask:0xf bank_mask:0xf
	v_mov_b32_e32 v15, v14
	s_nop 1
	v_permlane16_swap_b32_e32 v14, v15
	v_add_f32_e32 v14, v14, v15
	v_mov_b32_e32 v15, v14
	s_nop 1
	v_permlane32_swap_b32_e32 v14, v15
	v_add_f32_e32 v14, v14, v15
	s_waitcnt lgkmcnt(0)
	v_fmamk_f32 v11, v14, 0xbb800000, v11
	v_fmamk_f32 v10, v14, 0xbb800000, v10
	v_fmamk_f32 v13, v14, 0xbb800000, v13
	v_fmac_f32_e32 v12, 0xbb800000, v14
	v_pk_mul_f32 v[14:15], v[12:13], v[12:13]
	v_pk_mul_f32 v[16:17], v[10:11], v[10:11]
	s_nop 0
	v_pk_mov_b32 v[18:19], v[16:17], v[14:15] op_sel:[1,0]
	v_mov_b32_e32 v17, v15
	v_pk_add_f32 v[14:15], v[18:19], v[16:17]
	s_nop 0
	v_add_f32_e32 v14, v14, v15
	s_nop 1
	v_add_f32_dpp v14, v14, v14 quad_perm:[1,0,3,2] row_mask:0xf bank_mask:0xf
	s_nop 1
	v_add_f32_dpp v14, v14, v14 quad_perm:[2,3,0,1] row_mask:0xf bank_mask:0xf
	s_nop 1
	v_add_f32_dpp v14, v14, v14 row_half_mirror row_mask:0xf bank_mask:0xf
	s_nop 1
	v_add_f32_dpp v14, v14, v14 row_mirror row_mask:0xf bank_mask:0xf
	v_mov_b32_e32 v15, v14
	s_nop 1
	v_permlane16_swap_b32_e32 v14, v15
	v_add_f32_e32 v14, v14, v15
	v_mov_b32_e32 v15, v14
	s_nop 1
	v_permlane32_swap_b32_e32 v14, v15
	v_add_f32_e32 v14, v14, v15
	s_waitcnt lgkmcnt(0)
	v_fmamk_f32 v14, v14, 0x3b800000, v235
	v_cmp_gt_f32_e32 vcc, s2, v14
	v_mul_f32_e32 v15, 0x4f800000, v14
	s_nop 0
	v_cndmask_b32_e32 v14, v14, v15, vcc
	v_sqrt_f32_e32 v15, v14
	s_nop 0
	v_add_u32_e32 v16, -1, v15
	v_fma_f32 v17, -v16, v15, v14
	v_cmp_ge_f32_e64 s[0:1], 0, v17
	v_add_u32_e32 v17, 1, v15
	s_nop 0
	v_cndmask_b32_e64 v16, v15, v16, s[0:1]
	v_fma_f32 v15, -v17, v15, v14
	v_cmp_lt_f32_e64 s[0:1], 0, v15
	s_nop 1
	v_cndmask_b32_e64 v15, v16, v17, s[0:1]
	v_mul_f32_e32 v16, 0x37800000, v15
	v_cndmask_b32_e32 v15, v15, v16, vcc
	v_cmp_class_f32_e32 vcc, v14, v232
	s_nop 1
	v_cndmask_b32_e32 v14, v15, v14, vcc
	v_div_scale_f32 v15, s[0:1], v14, v14, 1.0
	v_rcp_f32_e32 v16, v15
	s_nop 0
	v_fma_f32 v17, -v15, v16, 1.0
	v_fmac_f32_e32 v16, v17, v16
	v_div_scale_f32 v17, vcc, 1.0, v14, 1.0
	v_mul_f32_e32 v18, v17, v16
	v_fma_f32 v19, -v15, v18, v17
	v_fmac_f32_e32 v18, v19, v16
	v_fma_f32 v15, -v15, v18, v17
	v_div_fmas_f32 v15, v15, v16, v18
	v_div_fixup_f32 v14, v15, v14, 1.0
	v_pk_mul_f32 v[10:11], v[10:11], v[14:15] op_sel_hi:[1,0]
	v_pk_mul_f32 v[12:13], v[12:13], v[14:15] op_sel_hi:[1,0]
	v_pk_fma_f32 v[10:11], v[2:3], v[10:11], v[6:7]
	v_pk_fma_f32 v[12:13], v[4:5], v[12:13], v[8:9]
	v_mul_f32_e32 v14, 0xbfb8aa3b, v10
	v_mul_f32_e32 v15, 0xbfb8aa3b, v11
	v_exp_f32_e32 v14, v14
	v_exp_f32_e32 v15, v15
	v_add_f32_e32 v14, 1.0, v14
	v_add_f32_e32 v15, 1.0, v15
	v_rcp_f32_e32 v14, v14
	v_rcp_f32_e32 v15, v15
	s_nop 0
	v_pk_mul_f32 v[10:11], v[10:11], v[14:15]
	v_mul_f32_e32 v14, 0xbfb8aa3b, v12
	v_mul_f32_e32 v15, 0xbfb8aa3b, v13
	v_exp_f32_e32 v14, v14
	v_exp_f32_e32 v15, v15
	v_cvt_pk_f16_f32 v10, v10, v11
	v_add_f32_e32 v14, 1.0, v14
	v_add_f32_e32 v15, 1.0, v15
	v_rcp_f32_e32 v14, v14
	v_rcp_f32_e32 v15, v15
	s_nop 0
	v_pk_mul_f32 v[12:13], v[12:13], v[14:15]
	s_nop 0
	v_cvt_pk_f16_f32 v11, v12, v13
	v_add_u32_e32 v12, s50, v121
	v_ashrrev_i32_e32 v13, 31, v12
	v_lshlrev_b64 v[12:13], 11, v[12:13]
	v_lshl_add_u64 v[12:13], v[60:61], 0, v[12:13]
	flat_store_dwordx2 v[12:13], v[10:11]
	s_waitcnt lgkmcnt(0)
	s_barrier
	s_cbranch_scc0 .LBB0_429
